# n1 + MLA softmax first-half exps deferred into next region (fmamk write final p regs), first-iteration copy of MLA region A
# baseline (speedup 1.0000x reference)
.LBB0_762:
	ds_read_b128 v[64:67], v189 offset:49152
	ds_read_b128 v[68:71], v189 offset:57344
	ds_read_b128 v[236:239], v191 offset:49152
	ds_read_b128 v[240:243], v191 offset:57344
	ds_read_b128 v[244:247], v193 offset:49152
	ds_read_b128 v[248:251], v193 offset:57344
	s_add_i32 s9, s24, -1
	s_cmp_lt_u32 s9, 3
	s_cselect_b32 s100, s46, s68
	s_add_i32 s100, s100, s8
	s_ashr_i32 s101, s100, 31
	s_mul_hi_u32 s7, s100, s40
	s_mul_i32 s6, s100, s41
	s_add_u32 s7, s7, s6
	s_mul_i32 s6, s101, s40
	s_add_u32 s7, s7, s6
	s_mul_i32 s6, s100, s40
	s_lshl_b64 s[6:7], s[6:7], 1
	s_add_i32 s0, 0, 0x12800
	s_waitcnt lgkmcnt(5)
	v_mfma_f32_32x32x16_bf16 v[80:95], v[64:67], v[124:127], 0
	v_exp_f32_e32 v140, v140
	v_exp_f32_e32 v141, v141
	v_add_u32_e32 v211, s0, v198
	s_waitcnt lgkmcnt(4)
	v_mfma_f32_32x32x16_bf16 v[64:79], v[68:71], v[124:127], 0
	v_exp_f32_e32 v138, v138
	v_exp_f32_e32 v139, v139
	v_add_u32_e32 v210, s0, v200
	s_waitcnt lgkmcnt(3)
	v_mfma_f32_32x32x16_bf16 v[80:95], v[236:239], v[120:123], v[80:95]
	ds_read_b128 v[236:239], v195 offset:49152
	v_exp_f32_e32 v214, v130
	v_exp_f32_e32 v215, v131
	v_add_u32_e32 v216, s0, v202
	s_waitcnt lgkmcnt(3)
	v_mfma_f32_32x32x16_bf16 v[64:79], v[240:243], v[120:123], v[64:79]
	ds_read_b128 v[240:243], v195 offset:57344
	v_exp_f32_e32 v142, v142
	v_exp_f32_e32 v143, v143
	v_add_u32_e32 v217, s0, v204
	s_waitcnt lgkmcnt(3)
	v_mfma_f32_32x32x16_bf16 v[80:95], v[244:247], v[116:119], v[80:95]
	ds_read_b128 v[244:247], v196 offset:49152
	v_exp_f32_e32 v136, v136
	v_exp_f32_e32 v137, v137
	v_cvt_pk_bf16_f32 v130, v156, v158
	s_waitcnt lgkmcnt(3)
	v_mfma_f32_32x32x16_bf16 v[64:79], v[248:251], v[116:119], v[64:79]
	ds_read_b128 v[248:251], v196 offset:57344
	v_exp_f32_e32 v212, v132
	v_exp_f32_e32 v213, v133
	v_cvt_pk_bf16_f32 v131, v154, v155
	s_waitcnt lgkmcnt(3)
	v_mfma_f32_32x32x16_bf16 v[80:95], v[236:239], v[112:115], v[80:95]
	ds_read_b128 v[236:239], v194 offset:49152
	v_exp_f32_e32 v220, v128
	v_add_f32_e32 v128, 0, v159
	v_add_f32_e32 v128, v161, v128
	v_add_f32_e32 v128, v157, v128
	s_waitcnt lgkmcnt(3)
	v_mfma_f32_32x32x16_bf16 v[64:79], v[240:243], v[112:115], v[64:79]
	ds_read_b128 v[240:243], v194 offset:57344
	v_add_f32_e32 v128, v160, v128
	v_add_f32_e32 v128, v156, v128
	v_add_f32_e32 v128, v158, v128
	v_add_f32_e32 v128, v154, v128
	v_add_f32_e32 v128, v155, v128
	s_waitcnt lgkmcnt(3)
	v_mfma_f32_32x32x16_bf16 v[80:95], v[244:247], v[108:111], v[80:95]
	ds_read_b128 v[244:247], v192 offset:49152
	v_add_f32_e32 v128, v151, v128
	v_add_f32_e32 v128, v153, v128
	v_add_f32_e32 v128, v150, v128
	v_add_f32_e32 v128, v152, v128
	v_add_f32_e32 v128, v147, v128
	s_waitcnt lgkmcnt(3)
	v_mfma_f32_32x32x16_bf16 v[64:79], v[248:251], v[108:111], v[64:79]
	ds_read_b128 v[248:251], v192 offset:57344
	v_add_f32_e32 v128, v149, v128
	v_add_f32_e32 v128, v146, v128
	v_add_f32_e32 v128, v148, v128
	v_add_f32_e32 v128, v140, v128
	v_add_f32_e32 v128, v141, v128
	s_waitcnt lgkmcnt(3)
	v_mfma_f32_32x32x16_bf16 v[80:95], v[236:239], v[104:107], v[80:95]
	ds_read_b128 v[236:239], v190 offset:49152
	v_add_f32_e32 v128, v138, v128
	v_add_f32_e32 v128, v139, v128
	v_add_f32_e32 v128, v212, v128
	v_exp_f32_e32 v221, v129
	s_waitcnt lgkmcnt(3)
	v_mfma_f32_32x32x16_bf16 v[64:79], v[240:243], v[104:107], v[64:79]
	ds_read_b128 v[240:243], v190 offset:57344
	v_add_f32_e32 v128, v213, v128
	v_add_f32_e32 v128, v214, v128
	v_add_f32_e32 v128, v215, v128
	v_add_f32_e32 v128, v220, v128
	v_add_f32_e32 v128, v221, v128
	s_waitcnt lgkmcnt(3)
	v_mfma_f32_32x32x16_bf16 v[80:95], v[244:247], v[100:103], v[80:95]
	ds_read_b128 v[244:247], v211
	v_exp_f32_e32 v223, v134
	v_add_f32_e32 v128, v142, v128
	v_exp_f32_e32 v224, v135
	s_waitcnt lgkmcnt(3)
	v_mfma_f32_32x32x16_bf16 v[64:79], v[248:251], v[100:103], v[64:79]
	v_add_f32_e32 v128, v143, v128
	v_add_f32_e32 v128, v136, v128
	v_add_f32_e32 v128, v137, v128
	v_add_f32_e32 v128, v223, v128
	v_add_f32_e32 v218, v224, v128
	s_waitcnt lgkmcnt(2)
	v_mfma_f32_32x32x16_bf16 v[80:95], v[236:239], v[96:99], v[80:95]
	ds_read_b128 v[236:239], v211 offset:4096
	ds_read_b128 v[248:251], v182
	v_mov_b32_e32 v219, v218
	v_cvt_pk_bf16_f32 v128, v159, v161
	v_cvt_pk_bf16_f32 v129, v157, v160
	v_cvt_pk_bf16_f32 v132, v151, v153
	v_cvt_pk_bf16_f32 v133, v150, v152
	s_waitcnt lgkmcnt(3)
	v_mfma_f32_32x32x16_bf16 v[64:79], v[240:243], v[96:99], v[64:79]
	ds_read_b128 v[240:243], v210
	v_cvt_pk_bf16_f32 v134, v147, v149
	v_cvt_pk_bf16_f32 v135, v146, v148
	v_cvt_pk_bf16_f32 v154, v140, v141
	v_cvt_pk_bf16_f32 v155, v138, v139
	v_cvt_pk_bf16_f32 v156, v212, v213
	s_waitcnt lgkmcnt(1)
	v_mfma_f32_32x32x16_bf16 v[80:95], v[244:247], v[248:251], v[80:95]
	v_cvt_pk_bf16_f32 v157, v214, v215
	v_cvt_pk_bf16_f32 v220, v220, v221
	v_cvt_pk_bf16_f32 v221, v142, v143
	v_cvt_pk_bf16_f32 v222, v136, v137
	v_permlane32_swap_b32_e32 v218, v219
	v_mfma_f32_32x32x16_bf16 v[64:79], v[236:239], v[248:251], v[64:79]
	ds_read_b128 v[248:251], v210 offset:4096
	ds_read_b128 v[244:247], v182 offset:1024
	ds_read_b128 v[236:239], v216
	v_permlane32_swap_b32_e32 v128, v130
	v_cvt_pk_bf16_f32 v223, v223, v224
	v_permlane32_swap_b32_e32 v220, v222
	v_permlane32_swap_b32_e32 v129, v131
	v_permlane32_swap_b32_e32 v132, v134
	s_waitcnt lgkmcnt(1)
	v_mfma_f32_32x32x16_bf16 v[80:95], v[240:243], v[244:247], v[80:95]
	v_permlane32_swap_b32_e32 v133, v135
	v_permlane32_swap_b32_e32 v154, v156
	v_permlane32_swap_b32_e32 v155, v157
	v_permlane32_swap_b32_e32 v221, v223
	v_lshl_add_u64 v[136:137], s[6:7], 0, v[162:163]
	v_mfma_f32_32x32x16_bf16 v[64:79], v[248:251], v[244:247], v[64:79]
	ds_read_b128 v[244:247], v216 offset:4096
	ds_read_b128 v[240:243], v182 offset:2048
	ds_read_b128 v[248:251], v217
	v_lshl_add_u64 v[140:141], s[6:7], 0, v[166:167]
	v_lshl_add_u64 v[146:147], s[6:7], 0, v[168:169]
	v_lshl_add_u64 v[150:151], s[6:7], 0, v[170:171]
	v_lshl_add_u64 v[158:159], s[100:101], 0, v[164:165]
	v_mad_u64_u32 v[160:161], s[100:101], v158, s3, v[172:173]
	s_waitcnt lgkmcnt(1)
	v_mfma_f32_32x32x16_bf16 v[80:95], v[236:239], v[240:243], v[80:95]
	v_mad_i32_i24 v161, v159, s3, v161
	v_mfma_f32_32x32x16_bf16 v[64:79], v[244:247], v[240:243], v[64:79]
	ds_read_b128 v[240:243], v217 offset:4096
	ds_read_b128 v[236:239], v182 offset:3072
	ds_read_b64_tr_b16 v[224:225], v181 offset:0
	ds_read_b64_tr_b16 v[226:227], v181 offset:0x800
	ds_read_b64_tr_b16 v[232:233], v181 offset:0x1000
	ds_read_b64_tr_b16 v[234:235], v181 offset:0x1800
	s_waitcnt lgkmcnt(4)
	v_mfma_f32_32x32x16_bf16 v[80:95], v[248:251], v[236:239], v[80:95]
	v_mfma_f32_32x32x16_bf16 v[64:79], v[240:243], v[236:239], v[64:79]
	ds_read_b64_tr_b16 v[236:237], v181 offset:0x2000
	ds_read_b64_tr_b16 v[238:239], v181 offset:0x2800
	ds_read_b64_tr_b16 v[240:241], v181 offset:0x3000
	ds_read_b64_tr_b16 v[242:243], v181 offset:0x3800
	ds_read_b64_tr_b16 v[212:213], v181 offset:0x200
	ds_read_b64_tr_b16 v[214:215], v181 offset:0xa00
	global_load_dwordx4 v[136:139], v[136:137], off
	global_load_dwordx4 v[140:143], v[140:141], off
	global_load_dwordx4 v[146:149], v[146:147], off
	global_load_dwordx4 v[150:153], v[150:151], off
	global_load_dwordx4 v[158:161], v[160:161], off
	s_waitcnt lgkmcnt(8)
	v_mfma_f32_32x32x16_bf16 v[0:15], v[128:131], v[224:227], v[0:15]
	ds_read_b64_tr_b16 v[224:225], v181 offset:0x1200
	ds_read_b64_tr_b16 v[226:227], v181 offset:0x1a00
	v_max_f32_e32 v250, v81, v81
	v_max_f32_e32 v251, v80, v80
	v_max_f32_e32 v250, v251, v250
	v_max3_f32 v250, v250, v82, v83
	v_max3_f32 v250, v250, v84, v85
	s_waitcnt lgkmcnt(8)
	v_mfma_f32_32x32x16_bf16 v[0:15], v[132:135], v[232:235], v[0:15]
	ds_read_b64_tr_b16 v[232:233], v181 offset:0x2200
	ds_read_b64_tr_b16 v[234:235], v181 offset:0x2a00
	v_max3_f32 v250, v250, v86, v87
	v_max3_f32 v250, v250, v88, v89
	v_max3_f32 v250, v250, v90, v91
	v_max3_f32 v250, v250, v92, v93
	v_max3_f32 v250, v250, v94, v95
	s_waitcnt lgkmcnt(8)
	v_mfma_f32_32x32x16_bf16 v[0:15], v[154:157], v[236:239], v[0:15]
	ds_read_b64_tr_b16 v[236:237], v181 offset:0x3200
	ds_read_b64_tr_b16 v[238:239], v181 offset:0x3a00
	v_max3_f32 v250, v250, v64, v65
	v_max3_f32 v250, v250, v66, v67
	v_max3_f32 v250, v250, v68, v69
	v_max3_f32 v250, v250, v70, v71
	v_max3_f32 v250, v250, v72, v73
	s_waitcnt lgkmcnt(8)
	v_mfma_f32_32x32x16_bf16 v[0:15], v[220:223], v[240:243], v[0:15]
	ds_read_b64_tr_b16 v[240:241], v181 offset:0x400
	ds_read_b64_tr_b16 v[242:243], v181 offset:0xc00
	v_max3_f32 v250, v250, v74, v75
	v_max3_f32 v250, v250, v76, v77
	v_max3_f32 v250, v250, v78, v79
	v_mov_b32_e32 v251, v250
	s_nop 1
	v_permlane32_swap_b32_e32 v250, v251
	s_waitcnt lgkmcnt(8)
	v_mfma_f32_32x32x16_bf16 v[48:63], v[128:131], v[212:215], v[48:63]
	ds_read_b64_tr_b16 v[212:213], v181 offset:0x1400
	ds_read_b64_tr_b16 v[214:215], v181 offset:0x1c00
	v_max_f32_e32 v251, v251, v251
	v_max_f32_e32 v250, v250, v250
	v_max_f32_e32 v250, v250, v251
	v_sub_f32_e32 v251, v250, v207
	v_cmp_ge_f32_e32 vcc, s94, v251
	s_waitcnt lgkmcnt(8)
	v_mfma_f32_32x32x16_bf16 v[48:63], v[132:135], v[224:227], v[48:63]
	ds_read_b64_tr_b16 v[224:225], v181 offset:0x2400
	ds_read_b64_tr_b16 v[226:227], v181 offset:0x2c00
	v_max_f32_e32 v251, v207, v207
	v_max_f32_e32 v250, v251, v250
	v_sub_f32_e32 v251, v207, v250
	v_mul_f32_e32 v251, 0x3dd53b94, v251
	s_waitcnt lgkmcnt(8)
	v_mfma_f32_32x32x16_bf16 v[48:63], v[154:157], v[232:235], v[48:63]
	ds_read_b64_tr_b16 v[232:233], v181 offset:0x3400
	ds_read_b64_tr_b16 v[234:235], v181 offset:0x3c00
	v_exp_f32_e32 v251, v251
	s_waitcnt lgkmcnt(8)
	v_mfma_f32_32x32x16_bf16 v[48:63], v[220:223], v[236:239], v[48:63]
	ds_read_b64_tr_b16 v[236:237], v181 offset:0x600
	ds_read_b64_tr_b16 v[238:239], v181 offset:0xe00
	s_waitcnt lgkmcnt(8)
	v_mfma_f32_32x32x16_bf16 v[32:47], v[128:131], v[240:243], v[32:47]
	ds_read_b64_tr_b16 v[240:241], v181 offset:0x1600
	ds_read_b64_tr_b16 v[242:243], v181 offset:0x1e00
	s_waitcnt lgkmcnt(8)
	v_mfma_f32_32x32x16_bf16 v[32:47], v[132:135], v[212:215], v[32:47]
	ds_read_b64_tr_b16 v[212:213], v181 offset:0x2600
	ds_read_b64_tr_b16 v[214:215], v181 offset:0x2e00
	s_waitcnt lgkmcnt(8)
	v_mfma_f32_32x32x16_bf16 v[32:47], v[154:157], v[224:227], v[32:47]
	ds_read_b64_tr_b16 v[224:225], v181 offset:0x3600
	ds_read_b64_tr_b16 v[226:227], v181 offset:0x3e00
	s_waitcnt lgkmcnt(8)
	v_mfma_f32_32x32x16_bf16 v[32:47], v[220:223], v[232:235], v[32:47]
	s_waitcnt lgkmcnt(6)
	v_mfma_f32_32x32x16_bf16 v[16:31], v[128:131], v[236:239], v[16:31]
	s_waitcnt lgkmcnt(4)
	v_mfma_f32_32x32x16_bf16 v[16:31], v[132:135], v[240:243], v[16:31]
	s_waitcnt lgkmcnt(2)
	v_mfma_f32_32x32x16_bf16 v[16:31], v[154:157], v[212:215], v[16:31]
	s_waitcnt lgkmcnt(0)
	v_mfma_f32_32x32x16_bf16 v[16:31], v[220:223], v[224:227], v[16:31]
	s_cmp_eq_u64 vcc, exec
	s_cselect_b64 s[6:7], -1, 0
	s_branch .Lmla_joinA
.Lmla_loopA:
	ds_read_b128 v[64:67], v189 offset:49152
	ds_read_b128 v[68:71], v189 offset:57344
	ds_read_b128 v[236:239], v191 offset:49152
	ds_read_b128 v[240:243], v191 offset:57344
	ds_read_b128 v[244:247], v193 offset:49152
	ds_read_b128 v[248:251], v193 offset:57344
	s_add_i32 s9, s24, -1
	s_cmp_lt_u32 s9, 3
	s_cselect_b32 s100, s46, s68
	s_add_i32 s100, s100, s8
	s_ashr_i32 s101, s100, 31
	s_mul_hi_u32 s7, s100, s40
	s_mul_i32 s6, s100, s41
	s_add_u32 s7, s7, s6
	s_mul_i32 s6, s101, s40
	s_add_u32 s7, s7, s6
	s_mul_i32 s6, s100, s40
	s_lshl_b64 s[6:7], s[6:7], 1
	s_add_i32 s0, 0, 0x12800
	s_waitcnt lgkmcnt(5)
	v_mfma_f32_32x32x16_bf16 v[80:95], v[64:67], v[124:127], 0
	v_exp_f32_e32 v159, v159
	v_exp_f32_e32 v161, v161
	v_add_u32_e32 v211, s0, v198
	s_waitcnt lgkmcnt(4)
	v_mfma_f32_32x32x16_bf16 v[64:79], v[68:71], v[124:127], 0
	v_exp_f32_e32 v157, v157
	v_exp_f32_e32 v160, v160
	v_add_u32_e32 v210, s0, v200
	s_waitcnt lgkmcnt(3)
	v_mfma_f32_32x32x16_bf16 v[80:95], v[236:239], v[120:123], v[80:95]
	ds_read_b128 v[236:239], v195 offset:49152
	v_exp_f32_e32 v156, v156
	v_exp_f32_e32 v158, v158
	v_add_u32_e32 v216, s0, v202
	s_waitcnt lgkmcnt(3)
	v_mfma_f32_32x32x16_bf16 v[64:79], v[240:243], v[120:123], v[64:79]
	ds_read_b128 v[240:243], v195 offset:57344
	v_exp_f32_e32 v154, v154
	v_exp_f32_e32 v155, v155
	v_add_u32_e32 v217, s0, v204
	s_waitcnt lgkmcnt(3)
	v_mfma_f32_32x32x16_bf16 v[80:95], v[244:247], v[116:119], v[80:95]
	ds_read_b128 v[244:247], v196 offset:49152
	v_exp_f32_e32 v151, v151
	v_exp_f32_e32 v153, v153
	s_waitcnt lgkmcnt(3)
	v_mfma_f32_32x32x16_bf16 v[64:79], v[248:251], v[116:119], v[64:79]
	ds_read_b128 v[248:251], v196 offset:57344
	v_exp_f32_e32 v150, v150
	v_exp_f32_e32 v152, v152
	s_waitcnt lgkmcnt(3)
	v_mfma_f32_32x32x16_bf16 v[80:95], v[236:239], v[112:115], v[80:95]
	ds_read_b128 v[236:239], v194 offset:49152
	v_exp_f32_e32 v147, v147
	v_exp_f32_e32 v149, v149
	s_waitcnt lgkmcnt(3)
	v_mfma_f32_32x32x16_bf16 v[64:79], v[240:243], v[112:115], v[64:79]
	ds_read_b128 v[240:243], v194 offset:57344
	v_exp_f32_e32 v146, v146
	v_exp_f32_e32 v148, v148
	s_waitcnt lgkmcnt(3)
	v_mfma_f32_32x32x16_bf16 v[80:95], v[244:247], v[108:111], v[80:95]
	ds_read_b128 v[244:247], v192 offset:49152
	v_exp_f32_e32 v140, v140
	v_exp_f32_e32 v141, v141
	s_waitcnt lgkmcnt(3)
	v_mfma_f32_32x32x16_bf16 v[64:79], v[248:251], v[108:111], v[64:79]
	ds_read_b128 v[248:251], v192 offset:57344
	v_exp_f32_e32 v138, v138
	v_exp_f32_e32 v139, v139
	s_waitcnt lgkmcnt(3)
	v_mfma_f32_32x32x16_bf16 v[80:95], v[236:239], v[104:107], v[80:95]
	ds_read_b128 v[236:239], v190 offset:49152
	v_exp_f32_e32 v214, v130
	v_exp_f32_e32 v215, v131
	v_cvt_pk_bf16_f32 v130, v156, v158
	s_waitcnt lgkmcnt(3)
	v_mfma_f32_32x32x16_bf16 v[64:79], v[240:243], v[104:107], v[64:79]
	ds_read_b128 v[240:243], v190 offset:57344
	v_exp_f32_e32 v142, v142
	v_exp_f32_e32 v143, v143
	v_cvt_pk_bf16_f32 v131, v154, v155
	s_waitcnt lgkmcnt(3)
	v_mfma_f32_32x32x16_bf16 v[80:95], v[244:247], v[100:103], v[80:95]
	ds_read_b128 v[244:247], v211
	v_exp_f32_e32 v136, v136
	v_exp_f32_e32 v137, v137
	s_nop 0
	v_cvt_pk_bf16_f32 v222, v136, v137
	s_waitcnt lgkmcnt(3)
	v_mfma_f32_32x32x16_bf16 v[64:79], v[248:251], v[100:103], v[64:79]
	v_exp_f32_e32 v212, v132
	v_exp_f32_e32 v213, v133
	v_cvt_pk_bf16_f32 v132, v151, v153
	s_waitcnt lgkmcnt(2)
	v_mfma_f32_32x32x16_bf16 v[80:95], v[236:239], v[96:99], v[80:95]
	ds_read_b128 v[236:239], v211 offset:4096
	ds_read_b128 v[248:251], v182
	v_exp_f32_e32 v220, v128
	v_add_f32_e32 v128, 0, v159
	v_add_f32_e32 v128, v161, v128
	v_add_f32_e32 v128, v157, v128
	s_waitcnt lgkmcnt(3)
	v_mfma_f32_32x32x16_bf16 v[64:79], v[240:243], v[96:99], v[64:79]
	ds_read_b128 v[240:243], v210
	v_add_f32_e32 v128, v160, v128
	v_add_f32_e32 v128, v156, v128
	v_add_f32_e32 v128, v158, v128
	v_add_f32_e32 v128, v154, v128
	v_add_f32_e32 v128, v155, v128
	s_waitcnt lgkmcnt(1)
	v_mfma_f32_32x32x16_bf16 v[80:95], v[244:247], v[248:251], v[80:95]
	v_add_f32_e32 v128, v151, v128
	v_add_f32_e32 v128, v153, v128
	v_add_f32_e32 v128, v150, v128
	v_add_f32_e32 v128, v152, v128
	v_add_f32_e32 v128, v147, v128
	v_mfma_f32_32x32x16_bf16 v[64:79], v[236:239], v[248:251], v[64:79]
	ds_read_b128 v[248:251], v210 offset:4096
	ds_read_b128 v[244:247], v182 offset:1024
	ds_read_b128 v[236:239], v216
	v_add_f32_e32 v128, v149, v128
	v_add_f32_e32 v128, v146, v128
	v_add_f32_e32 v128, v148, v128
	v_add_f32_e32 v128, v140, v128
	v_add_f32_e32 v128, v141, v128
	s_waitcnt lgkmcnt(1)
	v_mfma_f32_32x32x16_bf16 v[80:95], v[240:243], v[244:247], v[80:95]
	v_add_f32_e32 v128, v138, v128
	v_add_f32_e32 v128, v139, v128
	v_add_f32_e32 v128, v212, v128
	v_exp_f32_e32 v221, v129
	v_mfma_f32_32x32x16_bf16 v[64:79], v[248:251], v[244:247], v[64:79]
	ds_read_b128 v[244:247], v216 offset:4096
	ds_read_b128 v[240:243], v182 offset:2048
	ds_read_b128 v[248:251], v217
	v_add_f32_e32 v128, v213, v128
	v_add_f32_e32 v128, v214, v128
	v_add_f32_e32 v128, v215, v128
	v_add_f32_e32 v128, v220, v128
	v_add_f32_e32 v128, v221, v128
	s_waitcnt lgkmcnt(1)
	v_mfma_f32_32x32x16_bf16 v[80:95], v[236:239], v[240:243], v[80:95]
	v_exp_f32_e32 v223, v134
	v_add_f32_e32 v128, v142, v128
	v_exp_f32_e32 v224, v135
	v_mfma_f32_32x32x16_bf16 v[64:79], v[244:247], v[240:243], v[64:79]
	ds_read_b128 v[240:243], v217 offset:4096
	ds_read_b128 v[236:239], v182 offset:3072
	v_add_f32_e32 v128, v143, v128
	v_add_f32_e32 v128, v136, v128
	v_add_f32_e32 v128, v137, v128
	v_add_f32_e32 v128, v223, v128
	v_add_f32_e32 v218, v224, v128
	s_waitcnt lgkmcnt(0)
	v_mfma_f32_32x32x16_bf16 v[80:95], v[248:251], v[236:239], v[80:95]
	v_mov_b32_e32 v219, v218
	v_cvt_pk_bf16_f32 v128, v159, v161
	v_cvt_pk_bf16_f32 v129, v157, v160
	v_cvt_pk_bf16_f32 v133, v150, v152
	v_cvt_pk_bf16_f32 v134, v147, v149
	v_mfma_f32_32x32x16_bf16 v[64:79], v[240:243], v[236:239], v[64:79]
	v_cvt_pk_bf16_f32 v135, v146, v148
	v_cvt_pk_bf16_f32 v154, v140, v141
	v_cvt_pk_bf16_f32 v155, v138, v139
	v_cvt_pk_bf16_f32 v156, v212, v213
	v_cvt_pk_bf16_f32 v157, v214, v215
	v_lshl_add_u64 v[136:137], s[6:7], 0, v[162:163]
	global_load_dwordx4 v[136:139], v[136:137], off
	v_cvt_pk_bf16_f32 v220, v220, v221
	v_cvt_pk_bf16_f32 v221, v142, v143
	v_lshl_add_u64 v[140:141], s[6:7], 0, v[166:167]
	global_load_dwordx4 v[140:143], v[140:141], off
	v_lshl_add_u64 v[146:147], s[6:7], 0, v[168:169]
	global_load_dwordx4 v[146:149], v[146:147], off
	v_lshl_add_u64 v[150:151], s[6:7], 0, v[170:171]
	global_load_dwordx4 v[150:153], v[150:151], off
	v_lshl_add_u64 v[158:159], s[100:101], 0, v[164:165]
	v_mad_u64_u32 v[160:161], s[100:101], v158, s3, v[172:173]
	v_mad_i32_i24 v161, v159, s3, v161
	global_load_dwordx4 v[158:161], v[160:161], off
	v_permlane32_swap_b32_e32 v128, v130
	v_cvt_pk_bf16_f32 v223, v223, v224
	v_permlane32_swap_b32_e32 v129, v131
	ds_read_b64_tr_b16 v[224:225], v181 offset:0
	ds_read_b64_tr_b16 v[226:227], v181 offset:0x800
	s_waitcnt lgkmcnt(0)
	v_mfma_f32_32x32x16_bf16 v[0:15], v[128:131], v[224:227], v[0:15]
	ds_read_b64_tr_b16 v[232:233], v181 offset:0x1000
	ds_read_b64_tr_b16 v[234:235], v181 offset:0x1800
	ds_read_b64_tr_b16 v[236:237], v181 offset:0x2000
	ds_read_b64_tr_b16 v[238:239], v181 offset:0x2800
	ds_read_b64_tr_b16 v[240:241], v181 offset:0x3000
	ds_read_b64_tr_b16 v[242:243], v181 offset:0x3800
	ds_read_b64_tr_b16 v[212:213], v181 offset:0x200
	ds_read_b64_tr_b16 v[214:215], v181 offset:0xa00
	ds_read_b64_tr_b16 v[224:225], v181 offset:0x1200
	ds_read_b64_tr_b16 v[226:227], v181 offset:0x1a00
	v_permlane32_swap_b32_e32 v218, v219
	v_permlane32_swap_b32_e32 v220, v222
	v_permlane32_swap_b32_e32 v132, v134
	v_permlane32_swap_b32_e32 v133, v135
	v_permlane32_swap_b32_e32 v154, v156
	s_waitcnt lgkmcnt(8)
	v_mfma_f32_32x32x16_bf16 v[0:15], v[132:135], v[232:235], v[0:15]
	ds_read_b64_tr_b16 v[232:233], v181 offset:0x2200
	ds_read_b64_tr_b16 v[234:235], v181 offset:0x2a00
	v_permlane32_swap_b32_e32 v155, v157
	v_permlane32_swap_b32_e32 v221, v223
	v_max_f32_e32 v250, v81, v81
	v_max_f32_e32 v251, v80, v80
	v_max_f32_e32 v250, v251, v250
	s_waitcnt lgkmcnt(8)
	v_mfma_f32_32x32x16_bf16 v[0:15], v[154:157], v[236:239], v[0:15]
	ds_read_b64_tr_b16 v[236:237], v181 offset:0x3200
	ds_read_b64_tr_b16 v[238:239], v181 offset:0x3a00
	v_max3_f32 v250, v250, v82, v83
	v_max3_f32 v250, v250, v84, v85
	v_max3_f32 v250, v250, v86, v87
	v_max3_f32 v250, v250, v88, v89
	v_max3_f32 v250, v250, v90, v91
	s_waitcnt lgkmcnt(8)
	v_mfma_f32_32x32x16_bf16 v[0:15], v[220:223], v[240:243], v[0:15]
	ds_read_b64_tr_b16 v[240:241], v181 offset:0x400
	ds_read_b64_tr_b16 v[242:243], v181 offset:0xc00
	v_max3_f32 v250, v250, v92, v93
	v_max3_f32 v250, v250, v94, v95
	v_max3_f32 v250, v250, v64, v65
	v_max3_f32 v250, v250, v66, v67
	v_max3_f32 v250, v250, v68, v69
	s_waitcnt lgkmcnt(8)
	v_mfma_f32_32x32x16_bf16 v[48:63], v[128:131], v[212:215], v[48:63]
	ds_read_b64_tr_b16 v[212:213], v181 offset:0x1400
	ds_read_b64_tr_b16 v[214:215], v181 offset:0x1c00
	v_max3_f32 v250, v250, v70, v71
	v_max3_f32 v250, v250, v72, v73
	v_max3_f32 v250, v250, v74, v75
	v_max3_f32 v250, v250, v76, v77
	v_max3_f32 v250, v250, v78, v79
	s_waitcnt lgkmcnt(8)
	v_mfma_f32_32x32x16_bf16 v[48:63], v[132:135], v[224:227], v[48:63]
	ds_read_b64_tr_b16 v[224:225], v181 offset:0x2400
	ds_read_b64_tr_b16 v[226:227], v181 offset:0x2c00
	v_mov_b32_e32 v251, v250
	s_nop 1
	v_permlane32_swap_b32_e32 v250, v251
	v_max_f32_e32 v251, v251, v251
	v_max_f32_e32 v250, v250, v250
	v_max_f32_e32 v250, v250, v251
	s_waitcnt lgkmcnt(8)
	v_mfma_f32_32x32x16_bf16 v[48:63], v[154:157], v[232:235], v[48:63]
	ds_read_b64_tr_b16 v[232:233], v181 offset:0x3400
	ds_read_b64_tr_b16 v[234:235], v181 offset:0x3c00
	v_sub_f32_e32 v251, v250, v207
	v_cmp_ge_f32_e32 vcc, s94, v251
	v_max_f32_e32 v251, v207, v207
	v_max_f32_e32 v250, v251, v250
	v_sub_f32_e32 v251, v207, v250
	s_waitcnt lgkmcnt(8)
	v_mfma_f32_32x32x16_bf16 v[48:63], v[220:223], v[236:239], v[48:63]
	ds_read_b64_tr_b16 v[236:237], v181 offset:0x600
	ds_read_b64_tr_b16 v[238:239], v181 offset:0xe00
	v_mul_f32_e32 v251, 0x3dd53b94, v251
	v_exp_f32_e32 v251, v251
	s_waitcnt lgkmcnt(8)
	v_mfma_f32_32x32x16_bf16 v[32:47], v[128:131], v[240:243], v[32:47]
	ds_read_b64_tr_b16 v[240:241], v181 offset:0x1600
	ds_read_b64_tr_b16 v[242:243], v181 offset:0x1e00
	s_waitcnt lgkmcnt(8)
	v_mfma_f32_32x32x16_bf16 v[32:47], v[132:135], v[212:215], v[32:47]
	ds_read_b64_tr_b16 v[212:213], v181 offset:0x2600
	ds_read_b64_tr_b16 v[214:215], v181 offset:0x2e00
	s_waitcnt lgkmcnt(8)
	v_mfma_f32_32x32x16_bf16 v[32:47], v[154:157], v[224:227], v[32:47]
	ds_read_b64_tr_b16 v[224:225], v181 offset:0x3600
	ds_read_b64_tr_b16 v[226:227], v181 offset:0x3e00
	s_waitcnt lgkmcnt(8)
	v_mfma_f32_32x32x16_bf16 v[32:47], v[220:223], v[232:235], v[32:47]
	s_waitcnt lgkmcnt(6)
	v_mfma_f32_32x32x16_bf16 v[16:31], v[128:131], v[236:239], v[16:31]
	s_waitcnt lgkmcnt(4)
	v_mfma_f32_32x32x16_bf16 v[16:31], v[132:135], v[240:243], v[16:31]
	s_waitcnt lgkmcnt(2)
	v_mfma_f32_32x32x16_bf16 v[16:31], v[154:157], v[212:215], v[16:31]
	s_waitcnt lgkmcnt(0)
	v_mfma_f32_32x32x16_bf16 v[16:31], v[220:223], v[224:227], v[16:31]
	s_cmp_eq_u64 vcc, exec
	s_cselect_b64 s[6:7], -1, 0
.Lmla_joinA:
	s_barrier
	s_waitcnt vmcnt(0)
	v_cndmask_b32_e64 v220, v251, 1.0, s[6:7]
	v_add_u32_e32 v129, 0x10800, v208
	v_cmp_gt_f32_e32 vcc, 1.0, v220
	ds_write_b128 v187, v[146:149] offset:32768
	ds_write_b128 v188, v[150:153] offset:32768
	ds_write_b128 v129, v[158:161]
	ds_write_b128 v185, v[136:139]
	ds_write_b128 v186, v[140:143]
	s_nop 0
	s_nop 0
	s_nop 0
	s_nop 0
	s_nop 0
	s_cbranch_vccz .LBB0_766
	s_and_saveexec_b64 s[0:1], s[4:5]
	ds_write_b32 v183, v220 offset:128
	s_or_b64 exec, exec, s[0:1]
	s_waitcnt lgkmcnt(0)
	v_add_u32_e32 v129, v180, v144
	ds_read_b128 v[130:133], v129 offset:224
	ds_read_b128 v[134:137], v129 offset:192
	ds_read_b128 v[138:141], v129 offset:160
	ds_read_b128 v[146:149], v129 offset:128
	s_waitcnt lgkmcnt(3)
	v_pk_mul_f32 v[12:13], v[12:13], v[130:131]
	s_waitcnt lgkmcnt(2)
	v_pk_mul_f32 v[8:9], v[8:9], v[134:135]
	s_waitcnt lgkmcnt(1)
	v_pk_mul_f32 v[4:5], v[4:5], v[138:139]
	v_pk_mul_f32 v[14:15], v[14:15], v[132:133]
	v_pk_mul_f32 v[10:11], v[10:11], v[136:137]
	v_pk_mul_f32 v[6:7], v[6:7], v[140:141]
	s_waitcnt lgkmcnt(0)
	v_pk_mul_f32 v[2:3], v[2:3], v[148:149]
	v_pk_mul_f32 v[0:1], v[0:1], v[146:147]
	v_pk_mul_f32 v[60:61], v[60:61], v[130:131]
	v_pk_mul_f32 v[56:57], v[56:57], v[134:135]
	v_pk_mul_f32 v[52:53], v[52:53], v[138:139]
	v_pk_mul_f32 v[62:63], v[62:63], v[132:133]
	v_pk_mul_f32 v[58:59], v[58:59], v[136:137]
	v_pk_mul_f32 v[54:55], v[54:55], v[140:141]
	v_pk_mul_f32 v[50:51], v[50:51], v[148:149]
	v_pk_mul_f32 v[48:49], v[48:49], v[146:147]
	v_pk_mul_f32 v[44:45], v[44:45], v[130:131]
	v_pk_mul_f32 v[40:41], v[40:41], v[134:135]
	v_pk_mul_f32 v[36:37], v[36:37], v[138:139]
	v_pk_mul_f32 v[46:47], v[46:47], v[132:133]
	v_pk_mul_f32 v[42:43], v[42:43], v[136:137]
	v_pk_mul_f32 v[38:39], v[38:39], v[140:141]
	v_pk_mul_f32 v[34:35], v[34:35], v[148:149]
	v_pk_mul_f32 v[32:33], v[32:33], v[146:147]
	v_pk_mul_f32 v[28:29], v[28:29], v[130:131]
	v_pk_mul_f32 v[24:25], v[24:25], v[134:135]
	v_pk_mul_f32 v[20:21], v[20:21], v[138:139]
	v_pk_mul_f32 v[30:31], v[30:31], v[132:133]
	v_pk_mul_f32 v[26:27], v[26:27], v[136:137]
	v_pk_mul_f32 v[22:23], v[22:23], v[140:141]
	v_pk_mul_f32 v[18:19], v[18:19], v[148:149]
	v_pk_mul_f32 v[16:17], v[16:17], v[146:147]
.LBB0_766:
	v_cndmask_b32_e64 v207, v250, v207, s[6:7]
	v_mul_f32_e32 v146, 0xbdd53b94, v207
	v_fmamk_f32 v128, v80, 0x3dd53b94, v146
	v_fmamk_f32 v143, v81, 0x3dd53b94, v146
	v_fmamk_f32 v129, v82, 0x3dd53b94, v146
	v_fmamk_f32 v142, v83, 0x3dd53b94, v146
	v_fmamk_f32 v130, v84, 0x3dd53b94, v146
	v_fmamk_f32 v141, v85, 0x3dd53b94, v146
	v_fmamk_f32 v131, v86, 0x3dd53b94, v146
	v_fmamk_f32 v140, v87, 0x3dd53b94, v146
	v_fmamk_f32 v132, v88, 0x3dd53b94, v146
	v_fmamk_f32 v139, v89, 0x3dd53b94, v146
	v_fmamk_f32 v133, v90, 0x3dd53b94, v146
	v_fmamk_f32 v138, v91, 0x3dd53b94, v146
	v_fmamk_f32 v134, v92, 0x3dd53b94, v146
	v_fmamk_f32 v137, v93, 0x3dd53b94, v146
	v_fmamk_f32 v135, v94, 0x3dd53b94, v146
	v_fmamk_f32 v136, v95, 0x3dd53b94, v146
	v_fmamk_f32 v155, v64, 0x3dd53b94, v146
	v_fmamk_f32 v156, v65, 0x3dd53b94, v146
	v_fmamk_f32 v157, v66, 0x3dd53b94, v146
	v_fmamk_f32 v158, v67, 0x3dd53b94, v146
	v_fmamk_f32 v159, v68, 0x3dd53b94, v146
	v_fmamk_f32 v148, v69, 0x3dd53b94, v146
	v_fmamk_f32 v149, v70, 0x3dd53b94, v146
	v_fmamk_f32 v150, v71, 0x3dd53b94, v146
	v_fmamk_f32 v151, v72, 0x3dd53b94, v146
	v_fmamk_f32 v152, v73, 0x3dd53b94, v146
	v_fmamk_f32 v153, v74, 0x3dd53b94, v146
	v_fmamk_f32 v154, v75, 0x3dd53b94, v146
	v_fmamk_f32 v147, v76, 0x3dd53b94, v146
	v_fmamk_f32 v160, v77, 0x3dd53b94, v146
	v_fmamk_f32 v161, v78, 0x3dd53b94, v146
	v_fmac_f32_e32 v146, 0x3dd53b94, v79
	s_waitcnt lgkmcnt(2)
	s_barrier
	ds_read_b128 v[64:67], v189 offset:32768
	ds_read_b128 v[68:71], v189 offset:40960
	ds_read_b128 v[240:243], v191 offset:32768
	ds_read_b128 v[244:247], v191 offset:40960
	ds_read_b128 v[248:251], v193 offset:32768
	s_cmp_lt_u32 s9, 2
	s_cselect_b32 s100, s46, s68
	s_add_i32 s100, s100, s8
	s_add_i32 s100, s100, 64
	s_ashr_i32 s101, s100, 31
	s_mul_hi_u32 s7, s100, s40
	s_mul_i32 s6, s100, s41
	s_add_u32 s7, s7, s6
	s_mul_i32 s6, s101, s40
	s_add_u32 s7, s7, s6
	s_mul_i32 s6, s100, s40
	s_lshl_b64 s[6:7], s[6:7], 1
	s_waitcnt lgkmcnt(4)
	v_mfma_f32_32x32x16_bf16 v[80:95], v[64:67], v[124:127], 0
	v_exp_f32_e32 v128, v128
	v_exp_f32_e32 v143, v143
	s_waitcnt lgkmcnt(3)
	v_mfma_f32_32x32x16_bf16 v[64:79], v[68:71], v[124:127], 0
	v_exp_f32_e32 v129, v129
	v_exp_f32_e32 v142, v142
	s_waitcnt lgkmcnt(2)
	v_mfma_f32_32x32x16_bf16 v[80:95], v[240:243], v[120:123], v[80:95]
	ds_read_b128 v[240:243], v193 offset:40960
	v_exp_f32_e32 v130, v130
	v_exp_f32_e32 v141, v141
	s_waitcnt lgkmcnt(2)
	v_mfma_f32_32x32x16_bf16 v[64:79], v[244:247], v[120:123], v[64:79]
	ds_read_b128 v[244:247], v195 offset:32768
	v_exp_f32_e32 v131, v131
	v_exp_f32_e32 v140, v140
	s_waitcnt lgkmcnt(2)
	v_mfma_f32_32x32x16_bf16 v[80:95], v[248:251], v[116:119], v[80:95]
	ds_read_b128 v[248:251], v195 offset:40960
	v_exp_f32_e32 v132, v132
	v_exp_f32_e32 v139, v139
	s_waitcnt lgkmcnt(2)
	v_mfma_f32_32x32x16_bf16 v[64:79], v[240:243], v[116:119], v[64:79]
	ds_read_b128 v[240:243], v196 offset:32768
	v_exp_f32_e32 v133, v133
	v_exp_f32_e32 v138, v138
	s_waitcnt lgkmcnt(2)
	v_mfma_f32_32x32x16_bf16 v[80:95], v[244:247], v[112:115], v[80:95]
	ds_read_b128 v[244:247], v196 offset:40960
	v_exp_f32_e32 v134, v134
	v_exp_f32_e32 v137, v137
	s_waitcnt lgkmcnt(2)
	v_mfma_f32_32x32x16_bf16 v[64:79], v[248:251], v[112:115], v[64:79]
	ds_read_b128 v[248:251], v194 offset:32768
	v_exp_f32_e32 v135, v135
	v_exp_f32_e32 v136, v136
	s_waitcnt lgkmcnt(2)
	v_mfma_f32_32x32x16_bf16 v[80:95], v[240:243], v[108:111], v[80:95]
	ds_read_b128 v[240:243], v194 offset:40960
	v_exp_f32_e32 v212, v154
	v_add_f32_e32 v154, 0, v128
	v_add_f32_e32 v154, v143, v154
	v_add_f32_e32 v154, v129, v154
	s_waitcnt lgkmcnt(2)
	v_mfma_f32_32x32x16_bf16 v[64:79], v[244:247], v[108:111], v[64:79]
	ds_read_b128 v[244:247], v192 offset:32768
	v_add_f32_e32 v154, v142, v154
	v_add_f32_e32 v154, v130, v154
	v_add_f32_e32 v154, v141, v154
	v_add_f32_e32 v154, v131, v154
	v_add_f32_e32 v154, v140, v154
	s_waitcnt lgkmcnt(2)
	v_mfma_f32_32x32x16_bf16 v[80:95], v[248:251], v[104:107], v[80:95]
	ds_read_b128 v[248:251], v192 offset:40960
	v_add_f32_e32 v154, v132, v154
	v_add_f32_e32 v154, v139, v154
	v_add_f32_e32 v154, v133, v154
	v_add_f32_e32 v154, v138, v154
	v_add_f32_e32 v154, v134, v154
	s_waitcnt lgkmcnt(2)
	v_mfma_f32_32x32x16_bf16 v[64:79], v[240:243], v[104:107], v[64:79]
	ds_read_b128 v[240:243], v190 offset:32768
	v_exp_f32_e32 v155, v155
	v_exp_f32_e32 v156, v156
	v_add_f32_e32 v154, v137, v154
	s_waitcnt lgkmcnt(2)
	v_mfma_f32_32x32x16_bf16 v[80:95], v[244:247], v[100:103], v[80:95]
	ds_read_b128 v[244:247], v190 offset:40960
	v_exp_f32_e32 v157, v157
	v_add_f32_e32 v154, v135, v154
	v_exp_f32_e32 v158, v158
	s_waitcnt lgkmcnt(2)
	v_mfma_f32_32x32x16_bf16 v[64:79], v[248:251], v[100:103], v[64:79]
	ds_read_b128 v[248:251], v199
	v_add_f32_e32 v154, v136, v154
	v_exp_f32_e32 v159, v159
	v_add_f32_e32 v154, v155, v154
	v_add_f32_e32 v154, v156, v154
	s_waitcnt lgkmcnt(2)
	v_mfma_f32_32x32x16_bf16 v[80:95], v[240:243], v[96:99], v[80:95]
	v_exp_f32_e32 v148, v148
	v_exp_f32_e32 v149, v149
	v_add_f32_e32 v154, v157, v154
	s_waitcnt lgkmcnt(1)
	v_mfma_f32_32x32x16_bf16 v[64:79], v[244:247], v[96:99], v[64:79]
	ds_read_b128 v[244:247], v199 offset:4096
	ds_read_b128 v[240:243], v182
	v_exp_f32_e32 v150, v150
	v_add_f32_e32 v154, v158, v154
	v_exp_f32_e32 v151, v151
	s_waitcnt lgkmcnt(0)
	v_mfma_f32_32x32x16_bf16 v[80:95], v[248:251], v[240:243], v[80:95]
	ds_read_b128 v[248:251], v201
	v_add_f32_e32 v154, v159, v154
	v_exp_f32_e32 v152, v152
	v_add_f32_e32 v154, v148, v154
	v_add_f32_e32 v154, v149, v154
	v_mfma_f32_32x32x16_bf16 v[64:79], v[244:247], v[240:243], v[64:79]
	ds_read_b128 v[244:247], v201 offset:4096
	ds_read_b128 v[240:243], v182 offset:1024
	v_exp_f32_e32 v153, v153
	v_add_f32_e32 v154, v150, v154
	v_exp_f32_e32 v147, v147
	s_waitcnt lgkmcnt(0)
	v_mfma_f32_32x32x16_bf16 v[80:95], v[248:251], v[240:243], v[80:95]
	ds_read_b128 v[248:251], v203
	v_add_f32_e32 v154, v151, v154
	v_exp_f32_e32 v160, v160
	v_add_f32_e32 v154, v152, v154
	v_add_f32_e32 v154, v153, v154
	v_mfma_f32_32x32x16_bf16 v[64:79], v[244:247], v[240:243], v[64:79]
	ds_read_b128 v[244:247], v203 offset:4096
	ds_read_b128 v[240:243], v182 offset:2048
	v_exp_f32_e32 v161, v161
	v_exp_f32_e32 v146, v146
	v_add_f32_e32 v154, v212, v154
	s_waitcnt lgkmcnt(0)
	v_mfma_f32_32x32x16_bf16 v[80:95], v[248:251], v[240:243], v[80:95]
	ds_read_b128 v[248:251], v205
	v_add_f32_e32 v154, v147, v154
	v_add_f32_e32 v154, v160, v154
	v_add_f32_e32 v154, v161, v154
	v_cvt_pk_bf16_f32 v128, v128, v143
	v_cvt_pk_bf16_f32 v129, v129, v142
	v_mfma_f32_32x32x16_bf16 v[64:79], v[244:247], v[240:243], v[64:79]
	ds_read_b128 v[244:247], v205 offset:4096
	ds_read_b128 v[240:243], v182 offset:3072
	ds_read_b64_tr_b16 v[232:233], v184 offset:0
	ds_read_b64_tr_b16 v[234:235], v184 offset:0x800
	ds_read_b64_tr_b16 v[236:237], v184 offset:0x1000
	ds_read_b64_tr_b16 v[238:239], v184 offset:0x1800
	v_cvt_pk_bf16_f32 v130, v130, v141
	v_cvt_pk_bf16_f32 v131, v131, v140
	v_cvt_pk_bf16_f32 v132, v132, v139
	v_cvt_pk_bf16_f32 v133, v133, v138
	v_add_f32_e32 v222, v146, v154
	s_waitcnt lgkmcnt(4)
	v_mfma_f32_32x32x16_bf16 v[80:95], v[248:251], v[240:243], v[80:95]
	v_mov_b32_e32 v223, v222
	s_nop 1
	v_permlane32_swap_b32_e32 v222, v223
	v_permlane32_swap_b32_e32 v128, v130
	v_cvt_pk_bf16_f32 v134, v134, v137
	v_cvt_pk_bf16_f32 v135, v135, v136
	v_mfma_f32_32x32x16_bf16 v[64:79], v[244:247], v[240:243], v[64:79]
	ds_read_b64_tr_b16 v[240:241], v184 offset:0x2000
	ds_read_b64_tr_b16 v[242:243], v184 offset:0x2800
	ds_read_b64_tr_b16 v[244:245], v184 offset:0x3000
	ds_read_b64_tr_b16 v[246:247], v184 offset:0x3800
	v_cvt_pk_bf16_f32 v154, v155, v156
	v_cvt_pk_bf16_f32 v155, v157, v158
	v_cvt_pk_bf16_f32 v156, v159, v148
	v_cvt_pk_bf16_f32 v157, v149, v150
	v_cvt_pk_bf16_f32 v224, v151, v152
	v_lshl_add_u64 v[136:137], s[6:7], 0, v[162:163]
	global_load_dwordx4 v[136:139], v[136:137], off
	v_lshl_add_u64 v[140:141], s[6:7], 0, v[166:167]
	global_load_dwordx4 v[140:143], v[140:141], off
	v_cvt_pk_bf16_f32 v226, v147, v160
	v_cvt_pk_bf16_f32 v227, v161, v146
	v_lshl_add_u64 v[146:147], s[6:7], 0, v[168:169]
	global_load_dwordx4 v[146:149], v[146:147], off
	v_cvt_pk_bf16_f32 v225, v153, v212
	v_lshl_add_u64 v[150:151], s[6:7], 0, v[170:171]
	global_load_dwordx4 v[150:153], v[150:151], off
	v_lshl_add_u64 v[158:159], s[100:101], 0, v[164:165]
	v_mad_u64_u32 v[160:161], s[100:101], v158, s3, v[172:173]
	v_mad_i32_i24 v161, v159, s3, v161
	global_load_dwordx4 v[158:161], v[160:161], off
	v_permlane32_swap_b32_e32 v129, v131
	s_waitcnt lgkmcnt(6)
	s_nop 0
	v_mfma_f32_32x32x16_bf16 v[0:15], v[128:131], v[232:235], v[0:15]
	ds_read_b64_tr_b16 v[232:233], v184 offset:0x200
	ds_read_b64_tr_b16 v[234:235], v184 offset:0xa00
	v_permlane32_swap_b32_e32 v132, v134
	v_permlane32_swap_b32_e32 v133, v135
	v_permlane32_swap_b32_e32 v154, v156
	v_permlane32_swap_b32_e32 v155, v157
	v_permlane32_swap_b32_e32 v224, v226
	s_waitcnt lgkmcnt(6)
	v_mfma_f32_32x32x16_bf16 v[0:15], v[132:135], v[236:239], v[0:15]
	ds_read_b64_tr_b16 v[236:237], v184 offset:0x1200
	ds_read_b64_tr_b16 v[238:239], v184 offset:0x1a00
	v_permlane32_swap_b32_e32 v225, v227
	v_max_f32_e32 v250, v81, v81
	v_max_f32_e32 v251, v80, v80
	v_max_f32_e32 v250, v251, v250
	v_max3_f32 v250, v250, v82, v83
	s_waitcnt lgkmcnt(6)
	v_mfma_f32_32x32x16_bf16 v[0:15], v[154:157], v[240:243], v[0:15]
	ds_read_b64_tr_b16 v[240:241], v184 offset:0x2200
	ds_read_b64_tr_b16 v[242:243], v184 offset:0x2a00
	v_max3_f32 v250, v250, v84, v85
	v_max3_f32 v250, v250, v86, v87
	v_max3_f32 v250, v250, v88, v89
	v_max3_f32 v250, v250, v90, v91
	v_max3_f32 v250, v250, v92, v93
	s_waitcnt lgkmcnt(6)
	v_mfma_f32_32x32x16_bf16 v[0:15], v[224:227], v[244:247], v[0:15]
	ds_read_b64_tr_b16 v[244:245], v184 offset:0x3200
	ds_read_b64_tr_b16 v[246:247], v184 offset:0x3a00
	v_max3_f32 v250, v250, v94, v95
	v_max3_f32 v250, v250, v64, v65
	v_max3_f32 v250, v250, v66, v67
	v_max3_f32 v250, v250, v68, v69
	v_max3_f32 v250, v250, v70, v71
	s_waitcnt lgkmcnt(6)
	v_mfma_f32_32x32x16_bf16 v[48:63], v[128:131], v[232:235], v[48:63]
	ds_read_b64_tr_b16 v[232:233], v184 offset:0x400
	ds_read_b64_tr_b16 v[234:235], v184 offset:0xc00
	v_max3_f32 v250, v250, v72, v73
	v_max3_f32 v250, v250, v74, v75
	v_max3_f32 v250, v250, v76, v77
	v_max3_f32 v250, v250, v78, v79
	v_mov_b32_e32 v251, v250
	s_waitcnt lgkmcnt(6)
	v_mfma_f32_32x32x16_bf16 v[48:63], v[132:135], v[236:239], v[48:63]
	ds_read_b64_tr_b16 v[236:237], v184 offset:0x1400
	ds_read_b64_tr_b16 v[238:239], v184 offset:0x1c00
	v_permlane32_swap_b32_e32 v250, v251
	v_max_f32_e32 v251, v251, v251
	v_max_f32_e32 v250, v250, v250
	v_max_f32_e32 v250, v250, v251
	v_sub_f32_e32 v251, v250, v207
	s_waitcnt lgkmcnt(6)
	v_mfma_f32_32x32x16_bf16 v[48:63], v[154:157], v[240:243], v[48:63]
	ds_read_b64_tr_b16 v[240:241], v184 offset:0x2400
	ds_read_b64_tr_b16 v[242:243], v184 offset:0x2c00
	v_cmp_ge_f32_e32 vcc, s94, v251
	v_max_f32_e32 v251, v207, v207
	v_max_f32_e32 v250, v251, v250
	v_sub_f32_e32 v251, v207, v250
	v_mul_f32_e32 v251, 0x3dd53b94, v251
	s_waitcnt lgkmcnt(6)
	v_mfma_f32_32x32x16_bf16 v[48:63], v[224:227], v[244:247], v[48:63]
	ds_read_b64_tr_b16 v[244:245], v184 offset:0x3400
	ds_read_b64_tr_b16 v[246:247], v184 offset:0x3c00
	v_exp_f32_e32 v251, v251
	s_waitcnt lgkmcnt(6)
	v_mfma_f32_32x32x16_bf16 v[32:47], v[128:131], v[232:235], v[32:47]
	ds_read_b64_tr_b16 v[232:233], v184 offset:0x600
	ds_read_b64_tr_b16 v[234:235], v184 offset:0xe00
	s_waitcnt lgkmcnt(6)
	v_mfma_f32_32x32x16_bf16 v[32:47], v[132:135], v[236:239], v[32:47]
	ds_read_b64_tr_b16 v[236:237], v184 offset:0x1600
	ds_read_b64_tr_b16 v[238:239], v184 offset:0x1e00
	s_waitcnt lgkmcnt(6)
	v_mfma_f32_32x32x16_bf16 v[32:47], v[154:157], v[240:243], v[32:47]
	ds_read_b64_tr_b16 v[240:241], v184 offset:0x2600
	ds_read_b64_tr_b16 v[242:243], v184 offset:0x2e00
	s_waitcnt lgkmcnt(6)
	v_mfma_f32_32x32x16_bf16 v[32:47], v[224:227], v[244:247], v[32:47]
	ds_read_b64_tr_b16 v[244:245], v184 offset:0x3600
	ds_read_b64_tr_b16 v[246:247], v184 offset:0x3e00
	s_waitcnt lgkmcnt(6)
	v_mfma_f32_32x32x16_bf16 v[16:31], v[128:131], v[232:235], v[16:31]
	s_waitcnt lgkmcnt(4)
	v_mfma_f32_32x32x16_bf16 v[16:31], v[132:135], v[236:239], v[16:31]
	s_waitcnt lgkmcnt(2)
	v_mfma_f32_32x32x16_bf16 v[16:31], v[154:157], v[240:243], v[16:31]
	s_waitcnt lgkmcnt(0)
	v_mfma_f32_32x32x16_bf16 v[16:31], v[224:227], v[244:247], v[16:31]
	s_cmp_eq_u64 vcc, exec
	s_cselect_b64 s[6:7], -1, 0
	s_barrier
	s_waitcnt vmcnt(0)
	v_cndmask_b32_e64 v221, v251, 1.0, s[6:7]
	v_cmp_gt_f32_e32 vcc, 1.0, v221
	ds_write_b128 v187, v[146:149] offset:49152
	ds_write_b128 v188, v[150:153] offset:49152
	ds_write_b128 v209, v[158:161]
	ds_write_b128 v185, v[136:139] offset:16384
	ds_write_b128 v186, v[140:143] offset:16384
	s_nop 0
	s_nop 0
	s_nop 0
	s_nop 0
	s_nop 0
	s_cbranch_vccz .LBB0_770
	s_and_saveexec_b64 s[0:1], s[4:5]
	ds_write_b32 v183, v221 offset:128
	s_or_b64 exec, exec, s[0:1]
	s_waitcnt lgkmcnt(0)
	v_add_u32_e32 v129, v180, v144
	ds_read_b128 v[130:133], v129 offset:224
	ds_read_b128 v[134:137], v129 offset:192
	ds_read_b128 v[138:141], v129 offset:160
	ds_read_b128 v[146:149], v129 offset:128
	s_waitcnt lgkmcnt(3)
	v_pk_mul_f32 v[12:13], v[12:13], v[130:131]
	s_waitcnt lgkmcnt(2)
	v_pk_mul_f32 v[8:9], v[8:9], v[134:135]
	s_waitcnt lgkmcnt(1)
	v_pk_mul_f32 v[4:5], v[4:5], v[138:139]
	v_pk_mul_f32 v[14:15], v[14:15], v[132:133]
	v_pk_mul_f32 v[10:11], v[10:11], v[136:137]
	v_pk_mul_f32 v[6:7], v[6:7], v[140:141]
	s_waitcnt lgkmcnt(0)
	v_pk_mul_f32 v[2:3], v[2:3], v[148:149]
	v_pk_mul_f32 v[0:1], v[0:1], v[146:147]
	v_pk_mul_f32 v[60:61], v[60:61], v[130:131]
	v_pk_mul_f32 v[56:57], v[56:57], v[134:135]
	v_pk_mul_f32 v[52:53], v[52:53], v[138:139]
	v_pk_mul_f32 v[62:63], v[62:63], v[132:133]
	v_pk_mul_f32 v[58:59], v[58:59], v[136:137]
	v_pk_mul_f32 v[54:55], v[54:55], v[140:141]
	v_pk_mul_f32 v[50:51], v[50:51], v[148:149]
	v_pk_mul_f32 v[48:49], v[48:49], v[146:147]
	v_pk_mul_f32 v[44:45], v[44:45], v[130:131]
	v_pk_mul_f32 v[40:41], v[40:41], v[134:135]
	v_pk_mul_f32 v[36:37], v[36:37], v[138:139]
	v_pk_mul_f32 v[46:47], v[46:47], v[132:133]
	v_pk_mul_f32 v[42:43], v[42:43], v[136:137]
	v_pk_mul_f32 v[38:39], v[38:39], v[140:141]
	v_pk_mul_f32 v[34:35], v[34:35], v[148:149]
	v_pk_mul_f32 v[32:33], v[32:33], v[146:147]
	v_pk_mul_f32 v[28:29], v[28:29], v[130:131]
	v_pk_mul_f32 v[24:25], v[24:25], v[134:135]
	v_pk_mul_f32 v[20:21], v[20:21], v[138:139]
	v_pk_mul_f32 v[30:31], v[30:31], v[132:133]
	v_pk_mul_f32 v[26:27], v[26:27], v[136:137]
	v_pk_mul_f32 v[22:23], v[22:23], v[140:141]
	v_pk_mul_f32 v[18:19], v[18:19], v[148:149]
	v_pk_mul_f32 v[16:17], v[16:17], v[146:147]
.LBB0_770:
	v_cndmask_b32_e64 v207, v250, v207, s[6:7]
	v_mul_f32_e32 v134, 0xbdd53b94, v207
	v_fmamk_f32 v159, v80, 0x3dd53b94, v134
	v_fmamk_f32 v161, v81, 0x3dd53b94, v134
	v_fmamk_f32 v157, v82, 0x3dd53b94, v134
	v_fmamk_f32 v160, v83, 0x3dd53b94, v134
	v_fmamk_f32 v156, v84, 0x3dd53b94, v134
	v_fmamk_f32 v158, v85, 0x3dd53b94, v134
	v_fmamk_f32 v154, v86, 0x3dd53b94, v134
	v_fmamk_f32 v155, v87, 0x3dd53b94, v134
	v_fmamk_f32 v151, v88, 0x3dd53b94, v134
	v_fmamk_f32 v153, v89, 0x3dd53b94, v134
	v_fmamk_f32 v150, v90, 0x3dd53b94, v134
	v_fmamk_f32 v152, v91, 0x3dd53b94, v134
	v_fmamk_f32 v147, v92, 0x3dd53b94, v134
	v_fmamk_f32 v149, v93, 0x3dd53b94, v134
	v_fmamk_f32 v146, v94, 0x3dd53b94, v134
	v_fmamk_f32 v148, v95, 0x3dd53b94, v134
	v_fma_f32 v140, v64, s76, v134
	v_fma_f32 v141, v65, s76, v134
	v_add_f32_e32 v252, v218, v219
	v_fmac_f32_e32 v252, v206, v197
	v_add_f32_e32 v197, v222, v223
	s_addk_i32 s8, 0x80
	s_add_i32 s24, s24, 2
	v_fma_f32 v138, v66, s76, v134
	v_fma_f32 v139, v67, s76, v134
	v_fma_f32 v132, v68, s76, v134
	v_fma_f32 v133, v69, s76, v134
	v_fma_f32 v130, v70, s76, v134
	v_fma_f32 v131, v71, s76, v134
	v_fma_f32 v128, v72, s76, v134
	v_fma_f32 v129, v73, s76, v134
	v_fma_f32 v142, v74, s76, v134
	v_fma_f32 v143, v75, s76, v134
	v_fma_f32 v136, v76, s76, v134
	v_fma_f32 v137, v77, s76, v134
	v_fma_f32 v135, v79, s76, v134
	v_fma_f32 v134, v78, s76, v134
	v_fmac_f32_e32 v197, v252, v220
	s_cmp_ge_u32 s24, s91
	s_waitcnt lgkmcnt(2)
	s_barrier
	s_cbranch_scc1 .Lmla_exit
	v_mov_b32_e32 v206, v221
	s_branch .Lmla_loopA
.Lmla_exit:
	v_exp_f32_e32 v159, v159
	v_exp_f32_e32 v161, v161
	v_exp_f32_e32 v157, v157
	v_exp_f32_e32 v160, v160
	v_exp_f32_e32 v156, v156
	v_exp_f32_e32 v158, v158
	v_exp_f32_e32 v154, v154
	v_exp_f32_e32 v155, v155
	v_exp_f32_e32 v151, v151
	v_exp_f32_e32 v153, v153
	v_exp_f32_e32 v150, v150
	v_exp_f32_e32 v152, v152
	v_exp_f32_e32 v147, v147
	v_exp_f32_e32 v149, v149
	v_exp_f32_e32 v146, v146
	v_exp_f32_e32 v148, v148
